# v38 + prep: weight-transpose loop software-pipelined by one tile, second row-scale load issued with the row loads (run 1)
# baseline (speedup 1.0000x reference)
.LBB0_5:
	s_or_b64 exec, exec, s[2:3]
	s_mov_b64 s[28:29], s[0:1]
	v_mov_b32_e32 v1, v252
	s_load_dwordx2 s[26:27], s[28:29], 0xc0
	s_mov_b32 s34, s18
	s_cmpk_gt_i32 s34, 0x35ff
	v_readfirstlane_b32 s33, v1
	s_cbranch_scc1 .LBB0_31
	s_waitcnt lgkmcnt(0)
	s_add_u32 s35, s26, 0x8000000
	s_addc_u32 s36, s27, 0
	s_lshl_b32 s37, s34, 6
	s_lshl_b32 s38, s20, 6
	s_lshl_b32 s39, s34, 2
	s_lshl_b32 s40, s20, 2
	s_lshl_b32 s41, s34, 4
	s_lshl_b32 s42, s20, 4
	s_movk_i32 s43, 0x800
	s_mov_b32 s3, 0
	v_mov_b32_e32 v11, 0
	s_movk_i32 s44, 0x104
	s_mov_b32 s56, 0
	s_branch .LBB0_8
.LBB0_7:
	s_cmp_lg_u32 s56, 0
	s_cbranch_scc1 .Lpp_w1
	s_waitcnt vmcnt(0)
	s_branch .Lpp_w2
.Lpp_w1:
	s_waitcnt vmcnt(1)
.Lpp_w2:
	v_pk_mul_f32 v[36:37], v[2:3], v[12:13] op_sel_hi:[1,0]
	v_pk_mul_f32 v[38:39], v[4:5], v[12:13] op_sel_hi:[1,0]
	v_pk_mul_f32 v[40:41], v[6:7], v[10:11] op_sel_hi:[1,0]
	v_pk_mul_f32 v[42:43], v[8:9], v[10:11] op_sel_hi:[1,0]
	v_ashrrev_i32_e32 v48, 3, v252
	v_lshlrev_b32_e32 v47, 3, v252
	v_and_b32_e32 v49, 56, v47
	v_add_u32_e32 v44, s45, v48
	v_ashrrev_i32_e32 v45, 31, v44
	v_mul_lo_u32 v52, s12, v45
	v_mul_lo_u32 v53, s13, v44
	v_mad_u64_u32 v[44:45], s[4:5], s12, v44, 0
	v_add3_u32 v45, v45, v52, v53
	v_lshl_add_u64 v[44:45], v[44:45], 1, s[8:9]
	v_lshl_add_u64 v[44:45], s[2:3], 1, v[44:45]
	v_lshlrev_b32_e32 v54, 1, v49
	v_mov_b32_e32 v55, 0
	v_lshl_add_u64 v[44:45], v[44:45], 0, v[54:55]
	v_mad_u64_u32 v[56:57], s[4:5], v18, s44, v[16:17]
	v_mov_b32_e32 v58, v20
	v_lshlrev_b32_e32 v47, 2, v48
	v_mul_u32_u24_e32 v50, 0x104, v49
	v_add3_u32 v51, 0, v47, v50
	s_mov_b32 s56, 1
	s_add_i32 s34, s34, s20
	s_add_i32 s37, s37, s38
	s_add_i32 s39, s39, s40
	s_add_i32 s41, s41, s42
	s_cmpk_gt_i32 s34, 0x35ff
	s_cselect_b32 s57, 1, 0
	s_cbranch_scc0 .LBB0_8
.Lpp_mid:
	ds_write2_b32 v58, v36, v37 offset1:1
	ds_write2_b32 v58, v38, v39 offset0:2 offset1:3
	ds_write2_b32 v56, v40, v41 offset1:1
	ds_write2_b32 v56, v42, v43 offset0:2 offset1:3
	s_waitcnt lgkmcnt(0)
	s_barrier
	ds_read2_b32 v[60:61], v51 offset1:65
	ds_read2_b32 v[62:63], v51 offset0:130 offset1:195
	v_add_u32_e32 v59, 0x400, v51
	ds_read2_b32 v[64:65], v59 offset0:4 offset1:69
	ds_read2_b32 v[66:67], v59 offset0:134 offset1:199
	s_waitcnt lgkmcnt(3)
	v_cvt_pk_bf16_f32 v68, v60, v61
	s_waitcnt lgkmcnt(2)
	v_cvt_pk_bf16_f32 v69, v62, v63
	s_waitcnt lgkmcnt(1)
	v_cvt_pk_bf16_f32 v70, v64, v65
	s_waitcnt lgkmcnt(0)
	v_cvt_pk_bf16_f32 v71, v66, v67
	global_store_dwordx4 v[44:45], v[68:71], off
	s_barrier
	s_cmp_lg_u32 s57, 0
	s_cbranch_scc1 .LBB0_31
	s_branch .LBB0_7

.LBB0_29:
	v_add_u32_e32 v8, 0x200, v13
	v_ashrrev_i32_e32 v18, 4, v8
	v_add_u32_e32 v14, s2, v18
	v_ashrrev_i32_e32 v15, 31, v14
	v_mul_lo_u32 v19, s30, v15
	v_mul_lo_u32 v20, s31, v14
	v_mad_u64_u32 v[8:9], s[6:7], s30, v14, 0
	v_add3_u32 v9, v9, v19, v20
	v_lshl_add_u64 v[6:7], v[8:9], 2, v[6:7]
	global_load_dwordx4 v[6:9], v[6:7], off
	v_lshl_add_u32 v16, v16, 2, 0
	v_mad_u64_u32 v[20:21], s[6:7], v17, s44, v[16:17]
	s_andn2_b64 vcc, exec, s[4:5]
	s_cbranch_vccnz .Lprep_nog
	v_lshl_add_u64 v[32:33], v[14:15], 2, s[14:15]
	global_load_dword v10, v[32:33], off
.Lprep_nog:
	s_cmp_lg_u32 s56, 0
	s_cbranch_scc1 .Lpp_mid
	s_branch .LBB0_7
